# attention: removed all per-section s_setprio flips (no static priority either)
# baseline (speedup 1.0000x reference)
; __device__ __forceinline__ void attn_unit(const Params& p, int b, int h, int qb, unsigned char* lds) {
;     const int tid = threadIdx.x, lane = tid & 63, r32 = lane & 31, hi = lane >> 5, wid = __builtin_amdgcn_readfirstlane(tid >> 6);
;     const bf16* qg = (const bf16*)(p.ws + WS_Q); const bf16* kn = (const bf16*)(p.ws + WS_KN); const bf16* kr = (const bf16*)(p.ws + WS_KR); const bf16* vt = (const bf16*)(p.ws + WS_VT);
;     bf16* mix = (bf16*)(p.ws + WS_MIX);
;     const int rowbase = b * SEQ, q0 = qb * 256;
;     const int qrow = rowbase + q0 + wid * 32 + r32, qpos = q0 + wid * 32 + r32;
.LBB0_472:
	v_readfirstlane_b32 s42, v208
	s_nop 3
	s_cmpk_gt_u32 s42, 0xff
	s_cbranch_scc1 .Lattn_prio_done
	s_setprio 0
